# w1 GEMM K-loop: 3 of the 6 LDS-DMA issues of each SP2 load segment moved into the middle of the following MFMA block (vmcnt 8->5)
# baseline (speedup 1.0000x reference)
.LBB0_1532:
	s_waitcnt lgkmcnt(0)
	s_barrier
	s_setprio 1
	s_waitcnt lgkmcnt(0)
	v_mfma_f32_16x16x32_bf16 v[66:69], v[150:153], v[190:193], v[66:69]
	v_mfma_f32_16x16x32_bf16 v[62:65], v[158:161], v[190:193], v[62:65]
	v_mfma_f32_16x16x32_bf16 v[50:53], v[150:153], v[182:185], v[50:53]
	v_mfma_f32_16x16x32_bf16 v[46:49], v[158:161], v[182:185], v[46:49]
	v_mfma_f32_16x16x32_bf16 v[34:37], v[150:153], v[174:177], v[34:37]
	v_mfma_f32_16x16x32_bf16 v[30:33], v[158:161], v[174:177], v[30:33]
	v_mfma_f32_16x16x32_bf16 v[18:21], v[150:153], v[166:169], v[18:21]
	v_mfma_f32_16x16x32_bf16 v[10:13], v[158:161], v[166:169], v[10:13]
	v_mfma_f32_16x16x32_bf16 v[66:69], v[154:157], v[194:197], v[66:69]
	v_mfma_f32_16x16x32_bf16 v[62:65], v[162:165], v[194:197], v[62:65]
	v_mfma_f32_16x16x32_bf16 v[50:53], v[154:157], v[186:189], v[50:53]
	v_mfma_f32_16x16x32_bf16 v[46:49], v[162:165], v[186:189], v[46:49]
	v_mfma_f32_16x16x32_bf16 v[34:37], v[154:157], v[178:181], v[34:37]
	v_mfma_f32_16x16x32_bf16 v[30:33], v[162:165], v[178:181], v[30:33]
	v_mfma_f32_16x16x32_bf16 v[18:21], v[154:157], v[170:173], v[18:21]
	v_mfma_f32_16x16x32_bf16 v[10:13], v[162:165], v[170:173], v[10:13]
	s_setprio 0
	s_cbranch_vccnz .Lw1_mid_b
	s_mov_b32 m0, s64
	s_nop 0
	global_load_lds_dwordx4 v[212:213], off
	s_mov_b32 m0, s61
	s_nop 0
	global_load_lds_dwordx4 v[210:211], off
	s_mov_b32 m0, s62
	s_nop 0
	global_load_lds_dwordx4 v[208:209], off
.Lw1_mid_b:
	s_setprio 1
	v_mfma_f32_16x16x32_bf16 v[58:61], v[134:137], v[190:193], v[58:61]
	v_mfma_f32_16x16x32_bf16 v[54:57], v[142:145], v[190:193], v[54:57]
	v_mfma_f32_16x16x32_bf16 v[42:45], v[134:137], v[182:185], v[42:45]
	v_mfma_f32_16x16x32_bf16 v[38:41], v[142:145], v[182:185], v[38:41]
	v_mfma_f32_16x16x32_bf16 v[26:29], v[134:137], v[174:177], v[26:29]
	v_mfma_f32_16x16x32_bf16 v[22:25], v[142:145], v[174:177], v[22:25]
	v_mfma_f32_16x16x32_bf16 v[6:9], v[134:137], v[166:169], v[6:9]
	v_mfma_f32_16x16x32_bf16 v[2:5], v[142:145], v[166:169], v[2:5]
	v_mfma_f32_16x16x32_bf16 v[58:61], v[138:141], v[194:197], v[58:61]
	v_mfma_f32_16x16x32_bf16 v[54:57], v[146:149], v[194:197], v[54:57]
	v_mfma_f32_16x16x32_bf16 v[42:45], v[138:141], v[186:189], v[42:45]
	v_mfma_f32_16x16x32_bf16 v[38:41], v[146:149], v[186:189], v[38:41]
	v_mfma_f32_16x16x32_bf16 v[26:29], v[138:141], v[178:181], v[26:29]
	v_mfma_f32_16x16x32_bf16 v[22:25], v[146:149], v[178:181], v[22:25]
	v_mfma_f32_16x16x32_bf16 v[6:9], v[138:141], v[170:173], v[6:9]
	v_mfma_f32_16x16x32_bf16 v[2:5], v[146:149], v[170:173], v[2:5]
	s_setprio 0
	s_barrier
	s_add_i32 s33, s33, 2
	s_add_u32 s48, s48, 0x100
	s_addc_u32 s49, s49, 0
	s_add_u32 s70, s70, 0x100
	s_addc_u32 s71, s71, 0
	s_cmp_gt_u32 s33, 29
	s_cbranch_scc1 .LBB0_1543

.LBB0_1535:
	s_andn2_b64 vcc, exec, s[58:59]
	v_lshl_add_u64 v[216:217], s[50:51], 0, v[198:199]
	v_lshl_add_u64 v[212:213], s[50:51], 0, v[202:203]
	v_lshl_add_u64 v[210:211], s[52:53], 0, v[14:15]
	v_lshl_add_u64 v[208:209], s[52:53], 0, v[200:201]
	s_cbranch_vccnz .LBB0_1537
	s_mov_b32 m0, s23
	s_add_u32 s58, s50, 0x80000
	global_load_lds_dwordx4 v[216:217], off
	s_mov_b32 m0, s25
	s_addc_u32 s59, s51, 0
	global_load_lds_dwordx4 v[212:213], off
	v_lshl_add_u64 v[220:221], s[58:59], 0, v[198:199]
	s_mov_b32 m0, s28
	v_lshl_add_u64 v[222:223], s[58:59], 0, v[202:203]
	global_load_lds_dwordx4 v[220:221], off
	s_waitcnt vmcnt(5)
.LBB0_1537:
	s_waitcnt lgkmcnt(0)
	s_barrier
	s_setprio 1
	s_waitcnt lgkmcnt(0)
	v_mfma_f32_16x16x32_bf16 v[66:69], v[150:153], v[190:193], v[66:69]
	v_mfma_f32_16x16x32_bf16 v[62:65], v[158:161], v[190:193], v[62:65]
	v_mfma_f32_16x16x32_bf16 v[50:53], v[150:153], v[182:185], v[50:53]
	v_mfma_f32_16x16x32_bf16 v[46:49], v[158:161], v[182:185], v[46:49]
	v_mfma_f32_16x16x32_bf16 v[34:37], v[150:153], v[174:177], v[34:37]
	v_mfma_f32_16x16x32_bf16 v[30:33], v[158:161], v[174:177], v[30:33]
	v_mfma_f32_16x16x32_bf16 v[18:21], v[150:153], v[166:169], v[18:21]
	v_mfma_f32_16x16x32_bf16 v[10:13], v[158:161], v[166:169], v[10:13]
	v_mfma_f32_16x16x32_bf16 v[66:69], v[154:157], v[194:197], v[66:69]
	v_mfma_f32_16x16x32_bf16 v[62:65], v[162:165], v[194:197], v[62:65]
	v_mfma_f32_16x16x32_bf16 v[50:53], v[154:157], v[186:189], v[50:53]
	v_mfma_f32_16x16x32_bf16 v[46:49], v[162:165], v[186:189], v[46:49]
	v_mfma_f32_16x16x32_bf16 v[34:37], v[154:157], v[178:181], v[34:37]
	v_mfma_f32_16x16x32_bf16 v[30:33], v[162:165], v[178:181], v[30:33]
	v_mfma_f32_16x16x32_bf16 v[18:21], v[154:157], v[170:173], v[18:21]
	v_mfma_f32_16x16x32_bf16 v[10:13], v[162:165], v[170:173], v[10:13]
	s_setprio 0
	s_cbranch_vccnz .Lw1_mid_a
	s_mov_b32 m0, s29
	s_nop 0
	global_load_lds_dwordx4 v[222:223], off
	s_mov_b32 m0, s22
	s_nop 0
	global_load_lds_dwordx4 v[210:211], off
	s_mov_b32 m0, s36
	s_nop 0
	global_load_lds_dwordx4 v[208:209], off
.Lw1_mid_a:
	s_setprio 1
	v_mfma_f32_16x16x32_bf16 v[58:61], v[134:137], v[190:193], v[58:61]
	v_mfma_f32_16x16x32_bf16 v[54:57], v[142:145], v[190:193], v[54:57]
	v_mfma_f32_16x16x32_bf16 v[42:45], v[134:137], v[182:185], v[42:45]
	v_mfma_f32_16x16x32_bf16 v[38:41], v[142:145], v[182:185], v[38:41]
	v_mfma_f32_16x16x32_bf16 v[26:29], v[134:137], v[174:177], v[26:29]
	v_mfma_f32_16x16x32_bf16 v[22:25], v[142:145], v[174:177], v[22:25]
	v_mfma_f32_16x16x32_bf16 v[6:9], v[134:137], v[166:169], v[6:9]
	v_mfma_f32_16x16x32_bf16 v[2:5], v[142:145], v[166:169], v[2:5]
	v_mfma_f32_16x16x32_bf16 v[58:61], v[138:141], v[194:197], v[58:61]
	v_mfma_f32_16x16x32_bf16 v[54:57], v[146:149], v[194:197], v[54:57]
	v_mfma_f32_16x16x32_bf16 v[42:45], v[138:141], v[186:189], v[42:45]
	v_mfma_f32_16x16x32_bf16 v[38:41], v[146:149], v[186:189], v[38:41]
	v_mfma_f32_16x16x32_bf16 v[26:29], v[138:141], v[178:181], v[26:29]
	v_mfma_f32_16x16x32_bf16 v[22:25], v[146:149], v[178:181], v[22:25]
	v_mfma_f32_16x16x32_bf16 v[6:9], v[138:141], v[170:173], v[6:9]
	v_mfma_f32_16x16x32_bf16 v[2:5], v[146:149], v[170:173], v[2:5]
	s_setprio 0
	s_barrier
	v_add_u32_e32 v134, 0x18000, v218
	v_add_u32_e32 v146, 0x1c000, v218
	ds_read_b128 v[150:153], v134
	ds_read_b128 v[154:157], v134 offset:1024
	ds_read_b128 v[158:161], v134 offset:2048
	ds_read_b128 v[162:165], v134 offset:3072
	ds_read_b128 v[134:137], v146
	ds_read_b128 v[138:141], v146 offset:1024
	ds_read_b128 v[142:145], v146 offset:2048
	ds_read_b128 v[146:149], v146 offset:3072
	ds_read_b128 v[190:193], v219 offset:32768
	ds_read_b128 v[194:197], v219 offset:33792
	ds_read_b128 v[182:185], v219 offset:34816
	ds_read_b128 v[186:189], v219 offset:35840
	ds_read_b128 v[174:177], v219 offset:36864
	ds_read_b128 v[178:181], v219 offset:37888
	ds_read_b128 v[166:169], v219 offset:38912
	ds_read_b128 v[170:173], v219 offset:39936
	s_mov_b64 s[58:59], -1
	s_and_b64 vcc, exec, s[56:57]
	s_cbranch_vccz .LBB0_1539
	s_waitcnt vmcnt(0)
	s_mov_b64 s[58:59], 0

.LBB0_1541:
	s_waitcnt lgkmcnt(0)
	s_barrier
	s_setprio 1
	s_waitcnt lgkmcnt(0)
	v_mfma_f32_16x16x32_bf16 v[130:133], v[150:153], v[190:193], v[130:133]
	v_mfma_f32_16x16x32_bf16 v[126:129], v[158:161], v[190:193], v[126:129]
	v_mfma_f32_16x16x32_bf16 v[114:117], v[150:153], v[182:185], v[114:117]
	v_mfma_f32_16x16x32_bf16 v[110:113], v[158:161], v[182:185], v[110:113]
	v_mfma_f32_16x16x32_bf16 v[98:101], v[150:153], v[174:177], v[98:101]
	v_mfma_f32_16x16x32_bf16 v[94:97], v[158:161], v[174:177], v[94:97]
	v_mfma_f32_16x16x32_bf16 v[82:85], v[150:153], v[166:169], v[82:85]
	v_mfma_f32_16x16x32_bf16 v[78:81], v[158:161], v[166:169], v[78:81]
	v_mfma_f32_16x16x32_bf16 v[130:133], v[154:157], v[194:197], v[130:133]
	v_mfma_f32_16x16x32_bf16 v[126:129], v[162:165], v[194:197], v[126:129]
	v_mfma_f32_16x16x32_bf16 v[114:117], v[154:157], v[186:189], v[114:117]
	v_mfma_f32_16x16x32_bf16 v[110:113], v[162:165], v[186:189], v[110:113]
	v_mfma_f32_16x16x32_bf16 v[98:101], v[154:157], v[178:181], v[98:101]
	v_mfma_f32_16x16x32_bf16 v[94:97], v[162:165], v[178:181], v[94:97]
	v_mfma_f32_16x16x32_bf16 v[82:85], v[154:157], v[170:173], v[82:85]
	v_mfma_f32_16x16x32_bf16 v[78:81], v[162:165], v[170:173], v[78:81]
	s_setprio 0
	s_setprio 1
	v_mfma_f32_16x16x32_bf16 v[122:125], v[134:137], v[190:193], v[122:125]
	v_mfma_f32_16x16x32_bf16 v[118:121], v[142:145], v[190:193], v[118:121]
	v_mfma_f32_16x16x32_bf16 v[106:109], v[134:137], v[182:185], v[106:109]
	v_mfma_f32_16x16x32_bf16 v[102:105], v[142:145], v[182:185], v[102:105]
	v_mfma_f32_16x16x32_bf16 v[90:93], v[134:137], v[174:177], v[90:93]
	v_mfma_f32_16x16x32_bf16 v[86:89], v[142:145], v[174:177], v[86:89]
	v_mfma_f32_16x16x32_bf16 v[74:77], v[134:137], v[166:169], v[74:77]
	v_mfma_f32_16x16x32_bf16 v[70:73], v[142:145], v[166:169], v[70:73]
	v_mfma_f32_16x16x32_bf16 v[122:125], v[138:141], v[194:197], v[122:125]
	v_mfma_f32_16x16x32_bf16 v[118:121], v[146:149], v[194:197], v[118:121]
	v_mfma_f32_16x16x32_bf16 v[106:109], v[138:141], v[186:189], v[106:109]
	v_mfma_f32_16x16x32_bf16 v[102:105], v[146:149], v[186:189], v[102:105]
	v_mfma_f32_16x16x32_bf16 v[90:93], v[138:141], v[178:181], v[90:93]
	v_mfma_f32_16x16x32_bf16 v[86:89], v[146:149], v[178:181], v[86:89]
	v_mfma_f32_16x16x32_bf16 v[74:77], v[138:141], v[170:173], v[74:77]
	v_mfma_f32_16x16x32_bf16 v[70:73], v[146:149], v[170:173], v[70:73]
	s_setprio 0
	s_barrier
	ds_read_b128 v[190:193], v219 offset:49152
	ds_read_b128 v[194:197], v219 offset:50176
	ds_read_b128 v[182:185], v219 offset:51200
	ds_read_b128 v[186:189], v219 offset:52224
	ds_read_b128 v[174:177], v219 offset:53248
	ds_read_b128 v[178:181], v219 offset:54272
	ds_read_b128 v[166:169], v219 offset:55296
	ds_read_b128 v[170:173], v219 offset:56320
	s_andn2_b64 vcc, exec, s[54:55]
	s_cbranch_vccnz .LBB0_1532
	s_mov_b32 m0, s47
	v_lshl_add_u64 v[216:217], v[216:217], 0, s[16:17]
	s_add_u32 s50, s50, 0x80080
	global_load_lds_dwordx4 v[216:217], off
	v_lshl_add_u64 v[212:213], v[212:213], 0, s[16:17]
	s_mov_b32 m0, s60
	s_addc_u32 s51, s51, 0
	global_load_lds_dwordx4 v[212:213], off
	v_lshl_add_u64 v[212:213], s[50:51], 0, v[198:199]
	s_mov_b32 m0, s63
	v_lshl_add_u64 v[210:211], v[210:211], 0, s[16:17]
	global_load_lds_dwordx4 v[212:213], off
	v_lshl_add_u64 v[212:213], s[50:51], 0, v[202:203]
	v_lshl_add_u64 v[208:209], v[208:209], 0, s[16:17]
	s_waitcnt vmcnt(5)
	s_branch .LBB0_1532
